# plus: sc1 write-through stores in the output-projection epilogue ahead of the grid barrier
# baseline (speedup 1.0000x reference)
; #define GAS __attribute__((address_space(1)))
; __device__ __forceinline__ unsigned pk2(float lo, float hi) { unsigned r; asm("v_cvt_pk_bf16_f32 %0, %1, %2" : "=v"(r) : "v"(lo), "v"(hi)); return r; }
; __device__ __forceinline__ f32x4 bperm_f4(int src4, f32x4 v) { return (f32x4){bperm_f(src4, v.x), bperm_f(src4, v.y), bperm_f(src4, v.z), bperm_f(src4, v.w)}; }
;     __device__ __forceinline__ void operator()(const pg8::f32x4 (&acc)[2][2][4][2], const pg8::Unit& u, int wr, int wc, int fr, int fq) const {
;     ...
;             f32x4 xo[4][2][2];
; #pragma unroll
;             for (int m = 0; m < 4; ++m)
; #pragma unroll
;                 for (int bj = 0; bj < 2; ++bj) { const size_t off = (size_t)(row0 + ai * 128 + m * 16) * DM + col0 + bj * 128; xo[m][bj][0] = *(const GAS f32x4*)(xold + off); xo[m][bj][1] = *(const GAS f32x4*)(xold + off + 4); }
;             __builtin_amdgcn_sched_barrier(0);
; #pragma unroll
;             for (int m = 0; m < 4; ++m) {
;                 const int row = row0 + ai * 128 + m * 16; float ss = 0.f;
; #pragma unroll
;                 for (int bj = 0; bj < 2; ++bj) {
;                     const size_t off = (size_t)row * DM + col0 + bj * 128;
;                     const f32x4 x0 = xo[m][bj][0] + bperm_f4(src4, acc[ai][bj][m][0]), x1 = xo[m][bj][1] + bperm_f4(src4, acc[ai][bj][m][1]);
;                     *(GAS f32x4*)(out + off) = x0; *(GAS f32x4*)(out + off + 4) = x1;
;                     if (XN) { u32x4 w; w.x = pk2(x0.x, x0.y); w.y = pk2(x0.z, x0.w); w.z = pk2(x1.x, x1.y); w.w = pk2(x1.z, x1.w); *(GAS u32x4*)(XN + off) = w;
;                         ss += (x0.x * x0.x + x0.y * x0.y) + (x0.z * x0.z + x0.w * x0.w) + (x1.x * x1.x + x1.y * x1.y) + (x1.z * x1.z + x1.w * x1.w); }
;                 }
;                 if (XN) { ss += __shfl_xor(ss, 1); ss += __shfl_xor(ss, 2); if ((fr & 3) == 0) ((GAS float*)RS)[(size_t)row * 32 + u.pn * 4 + wc] = ss; }
.LBB0_1185:
	v_lshl_add_u32 v208, s45, 8, v234
	v_lshl_or_b32 v204, s44, 8, v235
	v_ashrrev_i32_e32 v205, 31, v204
	v_ashrrev_i32_e32 v209, 31, v208
	v_lshl_add_u64 v[206:207], v[204:205], 2, s[6:7]
	v_lshlrev_b64 v[122:123], 13, v[208:209]
	v_or_b32_e32 v214, 16, v208
	v_lshl_add_u64 v[122:123], v[206:207], 0, v[122:123]
	v_ashrrev_i32_e32 v215, 31, v214
	global_load_dwordx4 v[190:193], v[122:123], off offset:16
	global_load_dwordx4 v[238:241], v[122:123], off
	global_load_dwordx4 v[178:181], v[122:123], off offset:528
	global_load_dwordx4 v[182:185], v[122:123], off offset:512
	v_lshlrev_b64 v[122:123], 13, v[214:215]
	v_or_b32_e32 v212, 32, v208
	v_lshl_add_u64 v[122:123], v[206:207], 0, v[122:123]
	v_ashrrev_i32_e32 v213, 31, v212
	global_load_dwordx4 v[170:173], v[122:123], off offset:16
	global_load_dwordx4 v[174:177], v[122:123], off
	global_load_dwordx4 v[162:165], v[122:123], off offset:528
	global_load_dwordx4 v[166:169], v[122:123], off offset:512
	v_lshlrev_b64 v[122:123], 13, v[212:213]
	v_or_b32_e32 v210, 48, v208
	v_lshl_add_u64 v[122:123], v[206:207], 0, v[122:123]
	v_ashrrev_i32_e32 v211, 31, v210
	global_load_dwordx4 v[154:157], v[122:123], off offset:16
	global_load_dwordx4 v[158:161], v[122:123], off
	global_load_dwordx4 v[146:149], v[122:123], off offset:528
	global_load_dwordx4 v[150:153], v[122:123], off offset:512
	v_lshlrev_b64 v[122:123], 13, v[210:211]
	v_lshl_add_u64 v[126:127], v[206:207], 0, v[122:123]
	global_load_dwordx4 v[138:141], v[126:127], off offset:16
	global_load_dwordx4 v[142:145], v[126:127], off
	global_load_dwordx4 v[122:125], v[126:127], off offset:528
	s_nop 0
	global_load_dwordx4 v[126:129], v[126:127], off offset:512
	ds_bpermute_b32 v130, v233, v130
	ds_bpermute_b32 v131, v233, v131
	ds_bpermute_b32 v134, v233, v134
	ds_bpermute_b32 v135, v233, v135
	ds_bpermute_b32 v136, v233, v136
	ds_bpermute_b32 v137, v233, v137
	ds_bpermute_b32 v132, v233, v132
	ds_bpermute_b32 v133, v233, v133
	v_readlane_b32 s26, v254, 1
	v_lshlrev_b64 v[216:217], 11, v[208:209]
	v_readlane_b32 s27, v254, 2
	v_lshl_add_u64 v[216:217], v[216:217], 0, v[204:205]
	s_waitcnt vmcnt(0) lgkmcnt(0)
	v_pk_add_f32 v[130:131], v[190:191], v[130:131]
	v_cndmask_b32_e64 v190, 0, 1, s[26:27]
	v_pk_add_f32 v[136:137], v[240:241], v[136:137]
	v_pk_add_f32 v[134:135], v[238:239], v[134:135]
	v_pk_add_f32 v[132:133], v[192:193], v[132:133]
	v_lshl_add_u64 v[218:219], v[216:217], 2, s[8:9]
	v_cmp_ne_u32_e64 s[4:5], 1, v190
	s_andn2_b64 vcc, exec, s[26:27]
	v_mov_b32_e32 v237, 0
	global_store_dwordx4 v[218:219], v[134:137], off sc1
	global_store_dwordx4 v[218:219], v[130:133], off offset:16 sc1
	s_cbranch_vccnz .LBB0_1187
	v_cvt_pk_bf16_f32 v190, v134, v135
	v_cvt_pk_bf16_f32 v191, v136, v137
	v_lshl_add_u64 v[238:239], v[216:217], 1, s[12:13]
	v_pk_mul_f32 v[136:137], v[136:137], v[136:137]
	v_pk_mul_f32 v[134:135], v[134:135], v[134:135]
	v_cvt_pk_bf16_f32 v192, v130, v131
	v_cvt_pk_bf16_f32 v193, v132, v133
	global_store_dwordx4 v[238:239], v[190:193], off sc1
	v_pk_mul_f32 v[132:133], v[132:133], v[132:133]
	v_pk_mul_f32 v[130:131], v[130:131], v[130:131]
	v_pk_mov_b32 v[190:191], v[134:135], v[136:137] op_sel:[1,0]
	v_mov_b32_e32 v135, v137
	v_pk_add_f32 v[134:135], v[190:191], v[134:135]
	v_mov_b32_e32 v136, v132
	v_mov_b32_e32 v137, v130
	v_mov_b32_e32 v130, v133
	v_pk_add_f32 v[130:131], v[136:137], v[130:131]
	v_add_f32_e32 v132, v134, v135
	v_add_f32_e32 v131, v132, v131
	v_add_f32_e32 v237, v130, v131
.LBB0_1187:
	ds_bpermute_b32 v118, v233, v118
	ds_bpermute_b32 v119, v233, v119
	ds_bpermute_b32 v120, v233, v120
	ds_bpermute_b32 v121, v233, v121
	ds_bpermute_b32 v114, v233, v114
	ds_bpermute_b32 v116, v233, v116
	ds_bpermute_b32 v117, v233, v117
	ds_bpermute_b32 v115, v233, v115
	s_lshl_b32 s26, s44, 2
	s_ashr_i32 s27, s26, 31
	s_waitcnt lgkmcnt(4)
	v_pk_add_f32 v[120:121], v[184:185], v[120:121]
	v_pk_add_f32 v[118:119], v[182:183], v[118:119]
	s_waitcnt lgkmcnt(1)
	v_pk_add_f32 v[116:117], v[180:181], v[116:117]
	s_waitcnt lgkmcnt(0)
	v_pk_add_f32 v[114:115], v[178:179], v[114:115]
	s_and_b64 vcc, exec, s[4:5]
	global_store_dwordx4 v[218:219], v[118:121], off offset:512 sc1
	global_store_dwordx4 v[218:219], v[114:117], off offset:528 sc1
	s_cbranch_vccnz .LBB0_1191
	v_mul_f32_e32 v131, v119, v119
	v_mul_f32_e32 v132, v121, v121
	v_fmac_f32_e32 v131, v118, v118
	v_fmac_f32_e32 v132, v120, v120
	v_add_f32_e32 v131, v131, v132
	v_mul_f32_e32 v132, v115, v115
	v_mul_f32_e32 v130, v117, v117
	v_fmac_f32_e32 v132, v114, v114
	v_fmac_f32_e32 v130, v116, v116
	v_add_f32_e32 v131, v131, v132
	v_add_f32_e32 v130, v130, v131
	v_and_b32_e32 v131, 64, v225
	v_add_f32_e32 v132, v237, v130
	v_xor_b32_e32 v130, 1, v225
	v_add_u32_e32 v133, 64, v131
	v_cmp_lt_i32_e32 vcc, v130, v133
	v_cvt_pk_bf16_f32 v118, v118, v119
	v_cvt_pk_bf16_f32 v119, v120, v121
	v_cvt_pk_bf16_f32 v120, v114, v115
	v_xor_b32_e32 v115, 2, v225
	v_cvt_pk_bf16_f32 v121, v116, v117
	s_nop 0
	v_cndmask_b32_e32 v130, v225, v130, vcc
	v_lshlrev_b32_e32 v130, 2, v130
	ds_bpermute_b32 v134, v130, v132
	v_cmp_lt_i32_e32 vcc, v115, v133
	v_lshlrev_b64 v[130:131], 1, v[216:217]
	v_or_b32_e32 v130, 0x100, v130
	v_cndmask_b32_e32 v115, v225, v115, vcc
	s_waitcnt lgkmcnt(0)
	v_add_f32_e32 v114, v132, v134
	v_lshlrev_b32_e32 v115, 2, v115
	ds_bpermute_b32 v115, v115, v114
	v_lshl_add_u64 v[116:117], s[12:13], 0, v[130:131]
	global_store_dwordx4 v[116:117], v[118:121], off sc1
	s_and_saveexec_b64 s[28:29], s[0:1]
	s_cbranch_execz .LBB0_1190
	v_readlane_b32 s44, v253, 34
	v_lshlrev_b64 v[116:117], 7, v[208:209]
	v_readlane_b32 s45, v253, 35
	v_lshl_add_u64 v[116:117], s[14:15], 0, v[116:117]
	s_mov_b32 s19, s45
	v_lshl_add_u64 v[116:117], s[26:27], 2, v[116:117]
	s_lshl_b32 s44, s40, 2
	v_writelane_b32 v253, s18, 34
	v_lshl_add_u64 v[116:117], v[116:117], 0, s[44:45]
	s_waitcnt lgkmcnt(0)
	v_add_f32_e32 v114, v114, v115
	v_writelane_b32 v253, s19, 35
	global_store_dword v[116:117], v114, off

; #define GAS __attribute__((address_space(1)))
; __device__ __forceinline__ unsigned pk2(float lo, float hi) { unsigned r; asm("v_cvt_pk_bf16_f32 %0, %1, %2" : "=v"(r) : "v"(lo), "v"(hi)); return r; }
; __device__ __forceinline__ f32x4 bperm_f4(int src4, f32x4 v) { return (f32x4){bperm_f(src4, v.x), bperm_f(src4, v.y), bperm_f(src4, v.z), bperm_f(src4, v.w)}; }
;     __device__ __forceinline__ void operator()(const pg8::f32x4 (&acc)[2][2][4][2], const pg8::Unit& u, int wr, int wc, int fr, int fq) const {
;     ...
;             for (int m = 0; m < 4; ++m) {
;                 const int row = row0 + ai * 128 + m * 16; float ss = 0.f;
; #pragma unroll
;                 for (int bj = 0; bj < 2; ++bj) {
;                     const size_t off = (size_t)row * DM + col0 + bj * 128;
;                     const f32x4 x0 = xo[m][bj][0] + bperm_f4(src4, acc[ai][bj][m][0]), x1 = xo[m][bj][1] + bperm_f4(src4, acc[ai][bj][m][1]);
;                     *(GAS f32x4*)(out + off) = x0; *(GAS f32x4*)(out + off + 4) = x1;
;                     if (XN) { u32x4 w; w.x = pk2(x0.x, x0.y); w.y = pk2(x0.z, x0.w); w.z = pk2(x1.x, x1.y); w.w = pk2(x1.z, x1.w); *(GAS u32x4*)(XN + off) = w;
;                         ss += (x0.x * x0.x + x0.y * x0.y) + (x0.z * x0.z + x0.w * x0.w) + (x1.x * x1.x + x1.y * x1.y) + (x1.z * x1.z + x1.w * x1.w); }
;                 }
;                 if (XN) { ss += __shfl_xor(ss, 1); ss += __shfl_xor(ss, 2); if ((fr & 3) == 0) ((GAS float*)RS)[(size_t)row * 32 + u.pn * 4 + wc] = ss; }
.LBB0_1191:
	ds_bpermute_b32 v110, v233, v110
	ds_bpermute_b32 v111, v233, v111
	ds_bpermute_b32 v112, v233, v112
	ds_bpermute_b32 v113, v233, v113
	ds_bpermute_b32 v106, v233, v106
	ds_bpermute_b32 v108, v233, v108
	ds_bpermute_b32 v109, v233, v109
	ds_bpermute_b32 v107, v233, v107
	s_waitcnt lgkmcnt(8)
	v_lshlrev_b64 v[114:115], 11, v[214:215]
	v_lshl_add_u64 v[114:115], v[114:115], 0, v[204:205]
	s_waitcnt lgkmcnt(4)
	v_pk_add_f32 v[112:113], v[176:177], v[112:113]
	v_pk_add_f32 v[110:111], v[174:175], v[110:111]
	s_waitcnt lgkmcnt(1)
	v_pk_add_f32 v[108:109], v[172:173], v[108:109]
	s_waitcnt lgkmcnt(0)
	v_pk_add_f32 v[106:107], v[170:171], v[106:107]
	v_lshl_add_u64 v[116:117], v[114:115], 2, s[8:9]
	s_and_b64 vcc, exec, s[4:5]
	v_mov_b32_e32 v118, 0
	global_store_dwordx4 v[116:117], v[110:113], off sc1
	global_store_dwordx4 v[116:117], v[106:109], off offset:16 sc1
	s_cbranch_vccnz .LBB0_1193
	v_cvt_pk_bf16_f32 v118, v110, v111
	v_cvt_pk_bf16_f32 v119, v112, v113
	v_lshl_add_u64 v[130:131], v[114:115], 1, s[12:13]
	v_pk_mul_f32 v[112:113], v[112:113], v[112:113]
	v_pk_mul_f32 v[110:111], v[110:111], v[110:111]
	v_cvt_pk_bf16_f32 v120, v106, v107
	v_cvt_pk_bf16_f32 v121, v108, v109
	global_store_dwordx4 v[130:131], v[118:121], off sc1
	v_pk_mul_f32 v[108:109], v[108:109], v[108:109]
	v_pk_mul_f32 v[106:107], v[106:107], v[106:107]
	v_pk_mov_b32 v[118:119], v[110:111], v[112:113] op_sel:[1,0]
	v_mov_b32_e32 v111, v113
	v_pk_add_f32 v[110:111], v[118:119], v[110:111]
	v_mov_b32_e32 v112, v108
	v_mov_b32_e32 v113, v106
	v_mov_b32_e32 v106, v109
	v_pk_add_f32 v[106:107], v[112:113], v[106:107]
	v_add_f32_e32 v108, v110, v111
	v_add_f32_e32 v107, v108, v107
	v_add_f32_e32 v118, v106, v107
.LBB0_1193:
	ds_bpermute_b32 v102, v233, v102
	ds_bpermute_b32 v103, v233, v103
	ds_bpermute_b32 v104, v233, v104
	ds_bpermute_b32 v105, v233, v105
	ds_bpermute_b32 v98, v233, v98
	ds_bpermute_b32 v100, v233, v100
	ds_bpermute_b32 v101, v233, v101
	ds_bpermute_b32 v99, v233, v99
	s_waitcnt lgkmcnt(4)
	v_pk_add_f32 v[104:105], v[168:169], v[104:105]
	v_pk_add_f32 v[102:103], v[166:167], v[102:103]
	s_and_b64 vcc, exec, s[4:5]
	s_waitcnt lgkmcnt(1)
	v_pk_add_f32 v[100:101], v[164:165], v[100:101]
	s_waitcnt lgkmcnt(0)
	v_pk_add_f32 v[98:99], v[162:163], v[98:99]
	global_store_dwordx4 v[116:117], v[102:105], off offset:512 sc1
	global_store_dwordx4 v[116:117], v[98:101], off offset:528 sc1
	s_cbranch_vccnz .LBB0_1197
	v_mul_f32_e32 v107, v103, v103
	v_mul_f32_e32 v108, v105, v105
	v_fmac_f32_e32 v107, v102, v102
	v_fmac_f32_e32 v108, v104, v104
	v_add_f32_e32 v107, v107, v108
	v_mul_f32_e32 v108, v99, v99
	v_mul_f32_e32 v106, v101, v101
	v_fmac_f32_e32 v108, v98, v98
	v_fmac_f32_e32 v106, v100, v100
	v_add_f32_e32 v107, v107, v108
	v_add_f32_e32 v106, v106, v107
	v_and_b32_e32 v107, 64, v225
	v_add_f32_e32 v108, v118, v106
	v_xor_b32_e32 v106, 1, v225
	v_add_u32_e32 v109, 64, v107
	v_cmp_lt_i32_e32 vcc, v106, v109
	v_cvt_pk_bf16_f32 v102, v102, v103
	v_cvt_pk_bf16_f32 v103, v104, v105
	v_cvt_pk_bf16_f32 v104, v98, v99
	v_xor_b32_e32 v99, 2, v225
	v_cvt_pk_bf16_f32 v105, v100, v101
	s_nop 0
	v_cndmask_b32_e32 v106, v225, v106, vcc
	v_lshlrev_b32_e32 v106, 2, v106
	ds_bpermute_b32 v110, v106, v108
	v_cmp_lt_i32_e32 vcc, v99, v109
	v_lshlrev_b64 v[106:107], 1, v[114:115]
	v_or_b32_e32 v106, 0x100, v106
	v_cndmask_b32_e32 v99, v225, v99, vcc
	s_waitcnt lgkmcnt(0)
	v_add_f32_e32 v98, v108, v110
	v_lshlrev_b32_e32 v99, 2, v99
	ds_bpermute_b32 v99, v99, v98
	v_lshl_add_u64 v[100:101], s[12:13], 0, v[106:107]
	global_store_dwordx4 v[100:101], v[102:105], off sc1
	s_and_saveexec_b64 s[28:29], s[0:1]
	s_cbranch_execz .LBB0_1196
	v_readlane_b32 s44, v253, 34
	v_lshlrev_b64 v[100:101], 7, v[214:215]
	v_readlane_b32 s45, v253, 35
	v_lshl_add_u64 v[100:101], s[14:15], 0, v[100:101]
	s_mov_b32 s19, s45
	v_lshl_add_u64 v[100:101], s[26:27], 2, v[100:101]
	s_lshl_b32 s44, s40, 2
	v_writelane_b32 v253, s18, 34
	v_lshl_add_u64 v[100:101], v[100:101], 0, s[44:45]
	s_waitcnt lgkmcnt(0)
	v_add_f32_e32 v98, v98, v99
	v_writelane_b32 v253, s19, 35
	global_store_dword v[100:101], v98, off

; #define GAS __attribute__((address_space(1)))
; __device__ __forceinline__ unsigned pk2(float lo, float hi) { unsigned r; asm("v_cvt_pk_bf16_f32 %0, %1, %2" : "=v"(r) : "v"(lo), "v"(hi)); return r; }
; __device__ __forceinline__ f32x4 bperm_f4(int src4, f32x4 v) { return (f32x4){bperm_f(src4, v.x), bperm_f(src4, v.y), bperm_f(src4, v.z), bperm_f(src4, v.w)}; }
;     __device__ __forceinline__ void operator()(const pg8::f32x4 (&acc)[2][2][4][2], const pg8::Unit& u, int wr, int wc, int fr, int fq) const {
;     ...
;             for (int m = 0; m < 4; ++m) {
;                 const int row = row0 + ai * 128 + m * 16; float ss = 0.f;
; #pragma unroll
;                 for (int bj = 0; bj < 2; ++bj) {
;                     const size_t off = (size_t)row * DM + col0 + bj * 128;
;                     const f32x4 x0 = xo[m][bj][0] + bperm_f4(src4, acc[ai][bj][m][0]), x1 = xo[m][bj][1] + bperm_f4(src4, acc[ai][bj][m][1]);
;                     *(GAS f32x4*)(out + off) = x0; *(GAS f32x4*)(out + off + 4) = x1;
;                     if (XN) { u32x4 w; w.x = pk2(x0.x, x0.y); w.y = pk2(x0.z, x0.w); w.z = pk2(x1.x, x1.y); w.w = pk2(x1.z, x1.w); *(GAS u32x4*)(XN + off) = w;
;                         ss += (x0.x * x0.x + x0.y * x0.y) + (x0.z * x0.z + x0.w * x0.w) + (x1.x * x1.x + x1.y * x1.y) + (x1.z * x1.z + x1.w * x1.w); }
;                 }
;                 if (XN) { ss += __shfl_xor(ss, 1); ss += __shfl_xor(ss, 2); if ((fr & 3) == 0) ((GAS float*)RS)[(size_t)row * 32 + u.pn * 4 + wc] = ss; }
.LBB0_1197:
	ds_bpermute_b32 v94, v233, v94
	ds_bpermute_b32 v95, v233, v95
	ds_bpermute_b32 v96, v233, v96
	ds_bpermute_b32 v97, v233, v97
	ds_bpermute_b32 v90, v233, v90
	ds_bpermute_b32 v92, v233, v92
	ds_bpermute_b32 v93, v233, v93
	ds_bpermute_b32 v91, v233, v91
	s_waitcnt lgkmcnt(8)
	v_lshlrev_b64 v[98:99], 11, v[212:213]
	v_lshl_add_u64 v[98:99], v[98:99], 0, v[204:205]
	s_waitcnt lgkmcnt(4)
	v_pk_add_f32 v[96:97], v[160:161], v[96:97]
	v_pk_add_f32 v[94:95], v[158:159], v[94:95]
	s_waitcnt lgkmcnt(1)
	v_pk_add_f32 v[92:93], v[156:157], v[92:93]
	s_waitcnt lgkmcnt(0)
	v_pk_add_f32 v[90:91], v[154:155], v[90:91]
	v_lshl_add_u64 v[100:101], v[98:99], 2, s[8:9]
	s_and_b64 vcc, exec, s[4:5]
	v_mov_b32_e32 v102, 0
	global_store_dwordx4 v[100:101], v[94:97], off sc1
	global_store_dwordx4 v[100:101], v[90:93], off offset:16 sc1
	s_cbranch_vccnz .LBB0_1199
	v_cvt_pk_bf16_f32 v102, v94, v95
	v_cvt_pk_bf16_f32 v103, v96, v97
	v_lshl_add_u64 v[106:107], v[98:99], 1, s[12:13]
	v_pk_mul_f32 v[96:97], v[96:97], v[96:97]
	v_pk_mul_f32 v[94:95], v[94:95], v[94:95]
	v_cvt_pk_bf16_f32 v104, v90, v91
	v_cvt_pk_bf16_f32 v105, v92, v93
	global_store_dwordx4 v[106:107], v[102:105], off sc1
	v_pk_mul_f32 v[92:93], v[92:93], v[92:93]
	v_pk_mul_f32 v[90:91], v[90:91], v[90:91]
	v_pk_mov_b32 v[102:103], v[94:95], v[96:97] op_sel:[1,0]
	v_mov_b32_e32 v95, v97
	v_pk_add_f32 v[94:95], v[102:103], v[94:95]
	v_mov_b32_e32 v96, v92
	v_mov_b32_e32 v97, v90
	v_mov_b32_e32 v90, v93
	v_pk_add_f32 v[90:91], v[96:97], v[90:91]
	v_add_f32_e32 v92, v94, v95
	v_add_f32_e32 v91, v92, v91
	v_add_f32_e32 v102, v90, v91
.LBB0_1199:
	ds_bpermute_b32 v86, v233, v86
	ds_bpermute_b32 v87, v233, v87
	ds_bpermute_b32 v88, v233, v88
	ds_bpermute_b32 v89, v233, v89
	ds_bpermute_b32 v82, v233, v82
	ds_bpermute_b32 v84, v233, v84
	ds_bpermute_b32 v85, v233, v85
	ds_bpermute_b32 v83, v233, v83
	s_waitcnt lgkmcnt(4)
	v_pk_add_f32 v[88:89], v[152:153], v[88:89]
	v_pk_add_f32 v[86:87], v[150:151], v[86:87]
	s_and_b64 vcc, exec, s[4:5]
	s_waitcnt lgkmcnt(1)
	v_pk_add_f32 v[84:85], v[148:149], v[84:85]
	s_waitcnt lgkmcnt(0)
	v_pk_add_f32 v[82:83], v[146:147], v[82:83]
	global_store_dwordx4 v[100:101], v[86:89], off offset:512 sc1
	global_store_dwordx4 v[100:101], v[82:85], off offset:528 sc1
	s_cbranch_vccnz .LBB0_1203
	v_mul_f32_e32 v91, v87, v87
	v_mul_f32_e32 v92, v89, v89
	v_fmac_f32_e32 v91, v86, v86
	v_fmac_f32_e32 v92, v88, v88
	v_add_f32_e32 v91, v91, v92
	v_mul_f32_e32 v92, v83, v83
	v_mul_f32_e32 v90, v85, v85
	v_fmac_f32_e32 v92, v82, v82
	v_fmac_f32_e32 v90, v84, v84
	v_add_f32_e32 v91, v91, v92
	v_add_f32_e32 v90, v90, v91
	v_and_b32_e32 v91, 64, v225
	v_add_f32_e32 v92, v102, v90
	v_xor_b32_e32 v90, 1, v225
	v_add_u32_e32 v93, 64, v91
	v_cmp_lt_i32_e32 vcc, v90, v93
	v_cvt_pk_bf16_f32 v86, v86, v87
	v_cvt_pk_bf16_f32 v87, v88, v89
	v_cvt_pk_bf16_f32 v88, v82, v83
	v_xor_b32_e32 v83, 2, v225
	v_cvt_pk_bf16_f32 v89, v84, v85
	s_nop 0
	v_cndmask_b32_e32 v90, v225, v90, vcc
	v_lshlrev_b32_e32 v90, 2, v90
	ds_bpermute_b32 v94, v90, v92
	v_cmp_lt_i32_e32 vcc, v83, v93
	v_lshlrev_b64 v[90:91], 1, v[98:99]
	v_or_b32_e32 v90, 0x100, v90
	v_cndmask_b32_e32 v83, v225, v83, vcc
	s_waitcnt lgkmcnt(0)
	v_add_f32_e32 v82, v92, v94
	v_lshlrev_b32_e32 v83, 2, v83
	ds_bpermute_b32 v83, v83, v82
	v_lshl_add_u64 v[84:85], s[12:13], 0, v[90:91]
	global_store_dwordx4 v[84:85], v[86:89], off sc1
	s_and_saveexec_b64 s[28:29], s[0:1]
	s_cbranch_execz .LBB0_1202
	v_readlane_b32 s44, v253, 34
	v_lshlrev_b64 v[84:85], 7, v[212:213]
	v_readlane_b32 s45, v253, 35
	v_lshl_add_u64 v[84:85], s[14:15], 0, v[84:85]
	s_mov_b32 s19, s45
	v_lshl_add_u64 v[84:85], s[26:27], 2, v[84:85]
	s_lshl_b32 s44, s40, 2
	v_writelane_b32 v253, s18, 34
	v_lshl_add_u64 v[84:85], v[84:85], 0, s[44:45]
	s_waitcnt lgkmcnt(0)
	v_add_f32_e32 v82, v82, v83
	v_writelane_b32 v253, s19, 35
	global_store_dword v[84:85], v82, off

; #define GAS __attribute__((address_space(1)))
; __device__ __forceinline__ unsigned pk2(float lo, float hi) { unsigned r; asm("v_cvt_pk_bf16_f32 %0, %1, %2" : "=v"(r) : "v"(lo), "v"(hi)); return r; }
; __device__ __forceinline__ f32x4 bperm_f4(int src4, f32x4 v) { return (f32x4){bperm_f(src4, v.x), bperm_f(src4, v.y), bperm_f(src4, v.z), bperm_f(src4, v.w)}; }
;     __device__ __forceinline__ void operator()(const pg8::f32x4 (&acc)[2][2][4][2], const pg8::Unit& u, int wr, int wc, int fr, int fq) const {
;     ...
;             for (int m = 0; m < 4; ++m) {
;                 const int row = row0 + ai * 128 + m * 16; float ss = 0.f;
; #pragma unroll
;                 for (int bj = 0; bj < 2; ++bj) {
;                     const size_t off = (size_t)row * DM + col0 + bj * 128;
;                     const f32x4 x0 = xo[m][bj][0] + bperm_f4(src4, acc[ai][bj][m][0]), x1 = xo[m][bj][1] + bperm_f4(src4, acc[ai][bj][m][1]);
;                     *(GAS f32x4*)(out + off) = x0; *(GAS f32x4*)(out + off + 4) = x1;
;                     if (XN) { u32x4 w; w.x = pk2(x0.x, x0.y); w.y = pk2(x0.z, x0.w); w.z = pk2(x1.x, x1.y); w.w = pk2(x1.z, x1.w); *(GAS u32x4*)(XN + off) = w;
;                         ss += (x0.x * x0.x + x0.y * x0.y) + (x0.z * x0.z + x0.w * x0.w) + (x1.x * x1.x + x1.y * x1.y) + (x1.z * x1.z + x1.w * x1.w); }
;                 }
;                 if (XN) { ss += __shfl_xor(ss, 1); ss += __shfl_xor(ss, 2); if ((fr & 3) == 0) ((GAS float*)RS)[(size_t)row * 32 + u.pn * 4 + wc] = ss; }
.LBB0_1203:
	ds_bpermute_b32 v78, v233, v78
	ds_bpermute_b32 v79, v233, v79
	ds_bpermute_b32 v80, v233, v80
	ds_bpermute_b32 v81, v233, v81
	ds_bpermute_b32 v74, v233, v74
	ds_bpermute_b32 v76, v233, v76
	ds_bpermute_b32 v77, v233, v77
	ds_bpermute_b32 v75, v233, v75
	s_waitcnt lgkmcnt(8)
	v_lshlrev_b64 v[82:83], 11, v[210:211]
	v_lshl_add_u64 v[82:83], v[82:83], 0, v[204:205]
	s_waitcnt lgkmcnt(4)
	v_pk_add_f32 v[80:81], v[144:145], v[80:81]
	v_pk_add_f32 v[78:79], v[142:143], v[78:79]
	s_waitcnt lgkmcnt(1)
	v_pk_add_f32 v[76:77], v[140:141], v[76:77]
	s_waitcnt lgkmcnt(0)
	v_pk_add_f32 v[74:75], v[138:139], v[74:75]
	v_lshl_add_u64 v[84:85], v[82:83], 2, s[8:9]
	s_and_b64 vcc, exec, s[4:5]
	v_mov_b32_e32 v86, 0
	global_store_dwordx4 v[84:85], v[78:81], off sc1
	global_store_dwordx4 v[84:85], v[74:77], off offset:16 sc1
	s_cbranch_vccnz .LBB0_1205
	v_cvt_pk_bf16_f32 v86, v78, v79
	v_cvt_pk_bf16_f32 v87, v80, v81
	v_lshl_add_u64 v[90:91], v[82:83], 1, s[12:13]
	v_pk_mul_f32 v[80:81], v[80:81], v[80:81]
	v_pk_mul_f32 v[78:79], v[78:79], v[78:79]
	v_cvt_pk_bf16_f32 v88, v74, v75
	v_cvt_pk_bf16_f32 v89, v76, v77
	global_store_dwordx4 v[90:91], v[86:89], off sc1
	v_pk_mul_f32 v[76:77], v[76:77], v[76:77]
	v_pk_mul_f32 v[74:75], v[74:75], v[74:75]
	v_pk_mov_b32 v[86:87], v[78:79], v[80:81] op_sel:[1,0]
	v_mov_b32_e32 v79, v81
	v_pk_add_f32 v[78:79], v[86:87], v[78:79]
	v_mov_b32_e32 v80, v76
	v_mov_b32_e32 v81, v74
	v_mov_b32_e32 v74, v77
	v_pk_add_f32 v[74:75], v[80:81], v[74:75]
	v_add_f32_e32 v76, v78, v79
	v_add_f32_e32 v75, v76, v75
	v_add_f32_e32 v86, v74, v75
.LBB0_1205:
	ds_bpermute_b32 v70, v233, v70
	ds_bpermute_b32 v71, v233, v71
	ds_bpermute_b32 v72, v233, v72
	ds_bpermute_b32 v73, v233, v73
	ds_bpermute_b32 v66, v233, v66
	ds_bpermute_b32 v68, v233, v68
	ds_bpermute_b32 v69, v233, v69
	ds_bpermute_b32 v67, v233, v67
	s_waitcnt lgkmcnt(4)
	v_pk_add_f32 v[72:73], v[128:129], v[72:73]
	v_pk_add_f32 v[70:71], v[126:127], v[70:71]
	s_and_b64 vcc, exec, s[4:5]
	s_waitcnt lgkmcnt(1)
	v_pk_add_f32 v[68:69], v[124:125], v[68:69]
	s_waitcnt lgkmcnt(0)
	v_pk_add_f32 v[66:67], v[122:123], v[66:67]
	global_store_dwordx4 v[84:85], v[70:73], off offset:512 sc1
	global_store_dwordx4 v[84:85], v[66:69], off offset:528 sc1
	s_cbranch_vccnz .LBB0_1209
	v_mul_f32_e32 v75, v71, v71
	v_mul_f32_e32 v76, v73, v73
	v_fmac_f32_e32 v75, v70, v70
	v_fmac_f32_e32 v76, v72, v72
	v_add_f32_e32 v75, v75, v76
	v_mul_f32_e32 v76, v67, v67
	v_mul_f32_e32 v74, v69, v69
	v_fmac_f32_e32 v76, v66, v66
	v_fmac_f32_e32 v74, v68, v68
	v_add_f32_e32 v75, v75, v76
	v_add_f32_e32 v74, v74, v75
	v_and_b32_e32 v75, 64, v225
	v_add_f32_e32 v76, v86, v74
	v_xor_b32_e32 v74, 1, v225
	v_add_u32_e32 v77, 64, v75
	v_cmp_lt_i32_e32 vcc, v74, v77
	v_cvt_pk_bf16_f32 v70, v70, v71
	v_cvt_pk_bf16_f32 v71, v72, v73
	v_cvt_pk_bf16_f32 v72, v66, v67
	v_xor_b32_e32 v67, 2, v225
	v_cvt_pk_bf16_f32 v73, v68, v69
	s_nop 0
	v_cndmask_b32_e32 v74, v225, v74, vcc
	v_lshlrev_b32_e32 v74, 2, v74
	ds_bpermute_b32 v78, v74, v76
	v_cmp_lt_i32_e32 vcc, v67, v77
	v_lshlrev_b64 v[74:75], 1, v[82:83]
	v_or_b32_e32 v74, 0x100, v74
	v_cndmask_b32_e32 v67, v225, v67, vcc
	s_waitcnt lgkmcnt(0)
	v_add_f32_e32 v66, v76, v78
	v_lshlrev_b32_e32 v67, 2, v67
	ds_bpermute_b32 v67, v67, v66
	v_lshl_add_u64 v[68:69], s[12:13], 0, v[74:75]
	global_store_dwordx4 v[68:69], v[70:73], off sc1
	s_and_saveexec_b64 s[28:29], s[0:1]
	s_cbranch_execz .LBB0_1208
	v_readlane_b32 s44, v253, 34
	v_lshlrev_b64 v[68:69], 7, v[210:211]
	v_readlane_b32 s45, v253, 35
	v_lshl_add_u64 v[68:69], s[14:15], 0, v[68:69]
	s_mov_b32 s19, s45
	v_lshl_add_u64 v[68:69], s[26:27], 2, v[68:69]
	s_lshl_b32 s44, s40, 2
	v_writelane_b32 v253, s18, 34
	v_lshl_add_u64 v[68:69], v[68:69], 0, s[44:45]
	s_waitcnt lgkmcnt(0)
	v_add_f32_e32 v66, v66, v67
	v_writelane_b32 v253, s19, 35
	global_store_dword v[68:69], v66, off

; #define GAS __attribute__((address_space(1)))
; __device__ __forceinline__ unsigned pk2(float lo, float hi) { unsigned r; asm("v_cvt_pk_bf16_f32 %0, %1, %2" : "=v"(r) : "v"(lo), "v"(hi)); return r; }
; __device__ __forceinline__ f32x4 bperm_f4(int src4, f32x4 v) { return (f32x4){bperm_f(src4, v.x), bperm_f(src4, v.y), bperm_f(src4, v.z), bperm_f(src4, v.w)}; }
;     __device__ __forceinline__ void operator()(const pg8::f32x4 (&acc)[2][2][4][2], const pg8::Unit& u, int wr, int wc, int fr, int fq) const {
;     ...
;             for (int m = 0; m < 4; ++m)
; #pragma unroll
;                 for (int bj = 0; bj < 2; ++bj) { const size_t off = (size_t)(row0 + ai * 128 + m * 16) * DM + col0 + bj * 128; xo[m][bj][0] = *(const GAS f32x4*)(xold + off); xo[m][bj][1] = *(const GAS f32x4*)(xold + off + 4); }
;             __builtin_amdgcn_sched_barrier(0);
; #pragma unroll
;             for (int m = 0; m < 4; ++m) {
;                 const int row = row0 + ai * 128 + m * 16; float ss = 0.f;
; #pragma unroll
;                 for (int bj = 0; bj < 2; ++bj) {
;                     const size_t off = (size_t)row * DM + col0 + bj * 128;
;                     const f32x4 x0 = xo[m][bj][0] + bperm_f4(src4, acc[ai][bj][m][0]), x1 = xo[m][bj][1] + bperm_f4(src4, acc[ai][bj][m][1]);
;                     *(GAS f32x4*)(out + off) = x0; *(GAS f32x4*)(out + off + 4) = x1;
;                     if (XN) { u32x4 w; w.x = pk2(x0.x, x0.y); w.y = pk2(x0.z, x0.w); w.z = pk2(x1.x, x1.y); w.w = pk2(x1.z, x1.w); *(GAS u32x4*)(XN + off) = w;
;                         ss += (x0.x * x0.x + x0.y * x0.y) + (x0.z * x0.z + x0.w * x0.w) + (x1.x * x1.x + x1.y * x1.y) + (x1.z * x1.z + x1.w * x1.w); }
;                 }
;                 if (XN) { ss += __shfl_xor(ss, 1); ss += __shfl_xor(ss, 2); if ((fr & 3) == 0) ((GAS float*)RS)[(size_t)row * 32 + u.pn * 4 + wc] = ss; }
.LBB0_1209:
	v_add_u32_e32 v128, 0x80, v208
	v_ashrrev_i32_e32 v129, 31, v128
	s_waitcnt lgkmcnt(0)
	v_lshlrev_b64 v[66:67], 13, v[128:129]
	v_add_u32_e32 v126, 0x90, v208
	v_lshl_add_u64 v[66:67], v[206:207], 0, v[66:67]
	v_ashrrev_i32_e32 v127, 31, v126
	global_load_dwordx4 v[132:135], v[66:67], off offset:16
	global_load_dwordx4 v[136:139], v[66:67], off
	global_load_dwordx4 v[114:117], v[66:67], off offset:528
	global_load_dwordx4 v[118:121], v[66:67], off offset:512
	v_lshlrev_b64 v[66:67], 13, v[126:127]
	v_add_u32_e32 v124, 0xa0, v208
	v_lshl_add_u64 v[66:67], v[206:207], 0, v[66:67]
	v_ashrrev_i32_e32 v125, 31, v124
	global_load_dwordx4 v[106:109], v[66:67], off offset:16
	global_load_dwordx4 v[110:113], v[66:67], off
	global_load_dwordx4 v[98:101], v[66:67], off offset:528
	global_load_dwordx4 v[102:105], v[66:67], off offset:512
	v_lshlrev_b64 v[66:67], 13, v[124:125]
	v_add_u32_e32 v122, 0xb0, v208
	v_lshl_add_u64 v[66:67], v[206:207], 0, v[66:67]
	v_ashrrev_i32_e32 v123, 31, v122
	global_load_dwordx4 v[90:93], v[66:67], off offset:16
	global_load_dwordx4 v[94:97], v[66:67], off
	global_load_dwordx4 v[82:85], v[66:67], off offset:528
	global_load_dwordx4 v[86:89], v[66:67], off offset:512
	v_lshlrev_b64 v[66:67], 13, v[122:123]
	v_lshl_add_u64 v[70:71], v[206:207], 0, v[66:67]
	global_load_dwordx4 v[74:77], v[70:71], off offset:16
	global_load_dwordx4 v[78:81], v[70:71], off
	global_load_dwordx4 v[66:69], v[70:71], off offset:528
	s_nop 0
	global_load_dwordx4 v[70:73], v[70:71], off offset:512
	ds_bpermute_b32 v62, v233, v62
	ds_bpermute_b32 v63, v233, v63
	ds_bpermute_b32 v64, v233, v64
	ds_bpermute_b32 v65, v233, v65
	ds_bpermute_b32 v58, v233, v58
	ds_bpermute_b32 v59, v233, v59
	ds_bpermute_b32 v60, v233, v60
	ds_bpermute_b32 v61, v233, v61
	v_lshlrev_b64 v[130:131], 11, v[128:129]
	v_lshl_add_u64 v[130:131], v[130:131], 0, v[204:205]
	s_waitcnt vmcnt(14) lgkmcnt(6)
	v_pk_add_f32 v[62:63], v[136:137], v[62:63]
	s_waitcnt lgkmcnt(4)
	v_pk_add_f32 v[64:65], v[138:139], v[64:65]
	s_waitcnt lgkmcnt(2)
	v_pk_add_f32 v[58:59], v[132:133], v[58:59]
	s_waitcnt lgkmcnt(0)
	v_pk_add_f32 v[60:61], v[134:135], v[60:61]
	v_lshl_add_u64 v[132:133], v[130:131], 2, s[8:9]
	s_and_b64 vcc, exec, s[4:5]
	v_mov_b32_e32 v134, 0
	global_store_dwordx4 v[132:133], v[62:65], off sc1
	global_store_dwordx4 v[132:133], v[58:61], off offset:16 sc1
	s_cbranch_vccnz .LBB0_1211
	v_cvt_pk_bf16_f32 v134, v62, v63
	v_cvt_pk_bf16_f32 v135, v64, v65
	v_lshl_add_u64 v[138:139], v[130:131], 1, s[12:13]
	v_pk_mul_f32 v[64:65], v[64:65], v[64:65]
	v_pk_mul_f32 v[62:63], v[62:63], v[62:63]
	v_cvt_pk_bf16_f32 v136, v58, v59
	v_cvt_pk_bf16_f32 v137, v60, v61
	global_store_dwordx4 v[138:139], v[134:137], off sc1
	v_pk_mul_f32 v[60:61], v[60:61], v[60:61]
	v_pk_mul_f32 v[58:59], v[58:59], v[58:59]
	v_pk_mov_b32 v[134:135], v[62:63], v[64:65] op_sel:[1,0]
	v_mov_b32_e32 v63, v65
	v_pk_add_f32 v[62:63], v[134:135], v[62:63]
	v_mov_b32_e32 v64, v60
	v_mov_b32_e32 v65, v58
	v_mov_b32_e32 v58, v61
	v_pk_add_f32 v[58:59], v[64:65], v[58:59]
	v_add_f32_e32 v60, v62, v63
	v_add_f32_e32 v59, v60, v59
	v_add_f32_e32 v134, v58, v59
.LBB0_1211:
	ds_bpermute_b32 v54, v233, v54
	ds_bpermute_b32 v55, v233, v55
	ds_bpermute_b32 v56, v233, v56
	ds_bpermute_b32 v57, v233, v57
	ds_bpermute_b32 v50, v233, v50
	ds_bpermute_b32 v52, v233, v52
	ds_bpermute_b32 v53, v233, v53
	ds_bpermute_b32 v51, v233, v51
	s_waitcnt vmcnt(14) lgkmcnt(4)
	v_pk_add_f32 v[56:57], v[120:121], v[56:57]
	v_pk_add_f32 v[54:55], v[118:119], v[54:55]
	s_and_b64 vcc, exec, s[4:5]
	s_waitcnt lgkmcnt(1)
	v_pk_add_f32 v[52:53], v[116:117], v[52:53]
	s_waitcnt lgkmcnt(0)
	v_pk_add_f32 v[50:51], v[114:115], v[50:51]
	global_store_dwordx4 v[132:133], v[54:57], off offset:512 sc1
	global_store_dwordx4 v[132:133], v[50:53], off offset:528 sc1
	s_cbranch_vccnz .LBB0_1215
	v_mul_f32_e32 v59, v55, v55
	v_mul_f32_e32 v60, v57, v57
	v_fmac_f32_e32 v59, v54, v54
	v_fmac_f32_e32 v60, v56, v56
	v_add_f32_e32 v59, v59, v60
	v_mul_f32_e32 v60, v51, v51
	v_mul_f32_e32 v58, v53, v53
	v_fmac_f32_e32 v60, v50, v50
	v_fmac_f32_e32 v58, v52, v52
	v_add_f32_e32 v59, v59, v60
	v_add_f32_e32 v58, v58, v59
	v_and_b32_e32 v59, 64, v225
	v_add_f32_e32 v60, v134, v58
	v_xor_b32_e32 v58, 1, v225
	v_add_u32_e32 v61, 64, v59
	v_cmp_lt_i32_e32 vcc, v58, v61
	v_cvt_pk_bf16_f32 v54, v54, v55
	v_cvt_pk_bf16_f32 v55, v56, v57
	v_cvt_pk_bf16_f32 v56, v50, v51
	v_xor_b32_e32 v51, 2, v225
	v_cvt_pk_bf16_f32 v57, v52, v53
	s_nop 0
	v_cndmask_b32_e32 v58, v225, v58, vcc
	v_lshlrev_b32_e32 v58, 2, v58
	ds_bpermute_b32 v62, v58, v60
	v_cmp_lt_i32_e32 vcc, v51, v61
	v_lshlrev_b64 v[58:59], 1, v[130:131]
	v_or_b32_e32 v58, 0x100, v58
	v_cndmask_b32_e32 v51, v225, v51, vcc
	s_waitcnt lgkmcnt(0)
	v_add_f32_e32 v50, v60, v62
	v_lshlrev_b32_e32 v51, 2, v51
	ds_bpermute_b32 v51, v51, v50
	v_lshl_add_u64 v[52:53], s[12:13], 0, v[58:59]
	global_store_dwordx4 v[52:53], v[54:57], off sc1
	s_and_saveexec_b64 s[28:29], s[0:1]
	s_cbranch_execz .LBB0_1214
	v_readlane_b32 s44, v253, 34
	v_lshlrev_b64 v[52:53], 7, v[128:129]
	v_readlane_b32 s45, v253, 35
	v_lshl_add_u64 v[52:53], s[14:15], 0, v[52:53]
	s_mov_b32 s19, s45
	v_lshl_add_u64 v[52:53], s[26:27], 2, v[52:53]
	s_lshl_b32 s44, s40, 2
	v_writelane_b32 v253, s18, 34
	v_lshl_add_u64 v[52:53], v[52:53], 0, s[44:45]
	s_waitcnt lgkmcnt(0)
	v_add_f32_e32 v50, v50, v51
	v_writelane_b32 v253, s19, 35
	global_store_dword v[52:53], v50, off

; #define GAS __attribute__((address_space(1)))
; __device__ __forceinline__ unsigned pk2(float lo, float hi) { unsigned r; asm("v_cvt_pk_bf16_f32 %0, %1, %2" : "=v"(r) : "v"(lo), "v"(hi)); return r; }
; __device__ __forceinline__ f32x4 bperm_f4(int src4, f32x4 v) { return (f32x4){bperm_f(src4, v.x), bperm_f(src4, v.y), bperm_f(src4, v.z), bperm_f(src4, v.w)}; }
;     __device__ __forceinline__ void operator()(const pg8::f32x4 (&acc)[2][2][4][2], const pg8::Unit& u, int wr, int wc, int fr, int fq) const {
;     ...
;             for (int m = 0; m < 4; ++m) {
;                 const int row = row0 + ai * 128 + m * 16; float ss = 0.f;
; #pragma unroll
;                 for (int bj = 0; bj < 2; ++bj) {
;                     const size_t off = (size_t)row * DM + col0 + bj * 128;
;                     const f32x4 x0 = xo[m][bj][0] + bperm_f4(src4, acc[ai][bj][m][0]), x1 = xo[m][bj][1] + bperm_f4(src4, acc[ai][bj][m][1]);
;                     *(GAS f32x4*)(out + off) = x0; *(GAS f32x4*)(out + off + 4) = x1;
;                     if (XN) { u32x4 w; w.x = pk2(x0.x, x0.y); w.y = pk2(x0.z, x0.w); w.z = pk2(x1.x, x1.y); w.w = pk2(x1.z, x1.w); *(GAS u32x4*)(XN + off) = w;
;                         ss += (x0.x * x0.x + x0.y * x0.y) + (x0.z * x0.z + x0.w * x0.w) + (x1.x * x1.x + x1.y * x1.y) + (x1.z * x1.z + x1.w * x1.w); }
;                 }
;                 if (XN) { ss += __shfl_xor(ss, 1); ss += __shfl_xor(ss, 2); if ((fr & 3) == 0) ((GAS float*)RS)[(size_t)row * 32 + u.pn * 4 + wc] = ss; }
.LBB0_1215:
	ds_bpermute_b32 v46, v233, v46
	ds_bpermute_b32 v47, v233, v47
	ds_bpermute_b32 v48, v233, v48
	ds_bpermute_b32 v49, v233, v49
	ds_bpermute_b32 v42, v233, v42
	ds_bpermute_b32 v44, v233, v44
	ds_bpermute_b32 v45, v233, v45
	ds_bpermute_b32 v43, v233, v43
	s_waitcnt lgkmcnt(8)
	v_lshlrev_b64 v[50:51], 11, v[126:127]
	v_lshl_add_u64 v[50:51], v[50:51], 0, v[204:205]
	s_waitcnt vmcnt(14) lgkmcnt(4)
	v_pk_add_f32 v[48:49], v[112:113], v[48:49]
	v_pk_add_f32 v[46:47], v[110:111], v[46:47]
	s_waitcnt lgkmcnt(1)
	v_pk_add_f32 v[44:45], v[108:109], v[44:45]
	s_waitcnt lgkmcnt(0)
	v_pk_add_f32 v[42:43], v[106:107], v[42:43]
	v_lshl_add_u64 v[52:53], v[50:51], 2, s[8:9]
	s_and_b64 vcc, exec, s[4:5]
	v_mov_b32_e32 v54, 0
	global_store_dwordx4 v[52:53], v[46:49], off sc1
	global_store_dwordx4 v[52:53], v[42:45], off offset:16 sc1
	s_cbranch_vccnz .LBB0_1217
	v_cvt_pk_bf16_f32 v54, v46, v47
	v_cvt_pk_bf16_f32 v55, v48, v49
	v_lshl_add_u64 v[58:59], v[50:51], 1, s[12:13]
	v_pk_mul_f32 v[48:49], v[48:49], v[48:49]
	v_pk_mul_f32 v[46:47], v[46:47], v[46:47]
	v_cvt_pk_bf16_f32 v56, v42, v43
	v_cvt_pk_bf16_f32 v57, v44, v45
	global_store_dwordx4 v[58:59], v[54:57], off sc1
	v_pk_mul_f32 v[44:45], v[44:45], v[44:45]
	v_pk_mul_f32 v[42:43], v[42:43], v[42:43]
	v_pk_mov_b32 v[54:55], v[46:47], v[48:49] op_sel:[1,0]
	v_mov_b32_e32 v47, v49
	v_pk_add_f32 v[46:47], v[54:55], v[46:47]
	v_mov_b32_e32 v48, v44
	v_mov_b32_e32 v49, v42
	v_mov_b32_e32 v42, v45
	v_pk_add_f32 v[42:43], v[48:49], v[42:43]
	v_add_f32_e32 v44, v46, v47
	v_add_f32_e32 v43, v44, v43
	v_add_f32_e32 v54, v42, v43
.LBB0_1217:
	ds_bpermute_b32 v38, v233, v38
	ds_bpermute_b32 v39, v233, v39
	ds_bpermute_b32 v40, v233, v40
	ds_bpermute_b32 v41, v233, v41
	ds_bpermute_b32 v34, v233, v34
	ds_bpermute_b32 v36, v233, v36
	ds_bpermute_b32 v37, v233, v37
	ds_bpermute_b32 v35, v233, v35
	s_waitcnt vmcnt(14) lgkmcnt(4)
	v_pk_add_f32 v[40:41], v[104:105], v[40:41]
	v_pk_add_f32 v[38:39], v[102:103], v[38:39]
	s_and_b64 vcc, exec, s[4:5]
	s_waitcnt lgkmcnt(1)
	v_pk_add_f32 v[36:37], v[100:101], v[36:37]
	s_waitcnt lgkmcnt(0)
	v_pk_add_f32 v[34:35], v[98:99], v[34:35]
	global_store_dwordx4 v[52:53], v[38:41], off offset:512 sc1
	global_store_dwordx4 v[52:53], v[34:37], off offset:528 sc1
	s_cbranch_vccnz .LBB0_1221
	v_mul_f32_e32 v43, v39, v39
	v_mul_f32_e32 v44, v41, v41
	v_fmac_f32_e32 v43, v38, v38
	v_fmac_f32_e32 v44, v40, v40
	v_add_f32_e32 v43, v43, v44
	v_mul_f32_e32 v44, v35, v35
	v_mul_f32_e32 v42, v37, v37
	v_fmac_f32_e32 v44, v34, v34
	v_fmac_f32_e32 v42, v36, v36
	v_add_f32_e32 v43, v43, v44
	v_add_f32_e32 v42, v42, v43
	v_and_b32_e32 v43, 64, v225
	v_add_f32_e32 v44, v54, v42
	v_xor_b32_e32 v42, 1, v225
	v_add_u32_e32 v45, 64, v43
	v_cmp_lt_i32_e32 vcc, v42, v45
	v_cvt_pk_bf16_f32 v38, v38, v39
	v_cvt_pk_bf16_f32 v39, v40, v41
	v_cvt_pk_bf16_f32 v40, v34, v35
	v_xor_b32_e32 v35, 2, v225
	v_cvt_pk_bf16_f32 v41, v36, v37
	s_nop 0
	v_cndmask_b32_e32 v42, v225, v42, vcc
	v_lshlrev_b32_e32 v42, 2, v42
	ds_bpermute_b32 v46, v42, v44
	v_cmp_lt_i32_e32 vcc, v35, v45
	v_lshlrev_b64 v[42:43], 1, v[50:51]
	v_or_b32_e32 v42, 0x100, v42
	v_cndmask_b32_e32 v35, v225, v35, vcc
	s_waitcnt lgkmcnt(0)
	v_add_f32_e32 v34, v44, v46
	v_lshlrev_b32_e32 v35, 2, v35
	ds_bpermute_b32 v35, v35, v34
	v_lshl_add_u64 v[36:37], s[12:13], 0, v[42:43]
	global_store_dwordx4 v[36:37], v[38:41], off sc1
	s_and_saveexec_b64 s[28:29], s[0:1]
	s_cbranch_execz .LBB0_1220
	v_readlane_b32 s44, v253, 34
	v_lshlrev_b64 v[36:37], 7, v[126:127]
	v_readlane_b32 s45, v253, 35
	v_lshl_add_u64 v[36:37], s[14:15], 0, v[36:37]
	s_mov_b32 s19, s45
	v_lshl_add_u64 v[36:37], s[26:27], 2, v[36:37]
	s_lshl_b32 s44, s40, 2
	v_writelane_b32 v253, s18, 34
	v_lshl_add_u64 v[36:37], v[36:37], 0, s[44:45]
	s_waitcnt lgkmcnt(0)
	v_add_f32_e32 v34, v34, v35
	v_writelane_b32 v253, s19, 35
	global_store_dword v[36:37], v34, off

; #define GAS __attribute__((address_space(1)))
; __device__ __forceinline__ unsigned pk2(float lo, float hi) { unsigned r; asm("v_cvt_pk_bf16_f32 %0, %1, %2" : "=v"(r) : "v"(lo), "v"(hi)); return r; }
; __device__ __forceinline__ f32x4 bperm_f4(int src4, f32x4 v) { return (f32x4){bperm_f(src4, v.x), bperm_f(src4, v.y), bperm_f(src4, v.z), bperm_f(src4, v.w)}; }
;     __device__ __forceinline__ void operator()(const pg8::f32x4 (&acc)[2][2][4][2], const pg8::Unit& u, int wr, int wc, int fr, int fq) const {
;     ...
;             for (int m = 0; m < 4; ++m) {
;                 const int row = row0 + ai * 128 + m * 16; float ss = 0.f;
; #pragma unroll
;                 for (int bj = 0; bj < 2; ++bj) {
;                     const size_t off = (size_t)row * DM + col0 + bj * 128;
;                     const f32x4 x0 = xo[m][bj][0] + bperm_f4(src4, acc[ai][bj][m][0]), x1 = xo[m][bj][1] + bperm_f4(src4, acc[ai][bj][m][1]);
;                     *(GAS f32x4*)(out + off) = x0; *(GAS f32x4*)(out + off + 4) = x1;
;                     if (XN) { u32x4 w; w.x = pk2(x0.x, x0.y); w.y = pk2(x0.z, x0.w); w.z = pk2(x1.x, x1.y); w.w = pk2(x1.z, x1.w); *(GAS u32x4*)(XN + off) = w;
;                         ss += (x0.x * x0.x + x0.y * x0.y) + (x0.z * x0.z + x0.w * x0.w) + (x1.x * x1.x + x1.y * x1.y) + (x1.z * x1.z + x1.w * x1.w); }
;                 }
;                 if (XN) { ss += __shfl_xor(ss, 1); ss += __shfl_xor(ss, 2); if ((fr & 3) == 0) ((GAS float*)RS)[(size_t)row * 32 + u.pn * 4 + wc] = ss; }
.LBB0_1221:
	ds_bpermute_b32 v30, v233, v30
	ds_bpermute_b32 v31, v233, v31
	ds_bpermute_b32 v32, v233, v32
	ds_bpermute_b32 v33, v233, v33
	ds_bpermute_b32 v26, v233, v26
	ds_bpermute_b32 v28, v233, v28
	ds_bpermute_b32 v29, v233, v29
	ds_bpermute_b32 v27, v233, v27
	s_waitcnt lgkmcnt(8)
	v_lshlrev_b64 v[34:35], 11, v[124:125]
	v_lshl_add_u64 v[34:35], v[34:35], 0, v[204:205]
	s_waitcnt vmcnt(14) lgkmcnt(4)
	v_pk_add_f32 v[32:33], v[96:97], v[32:33]
	v_pk_add_f32 v[30:31], v[94:95], v[30:31]
	s_waitcnt lgkmcnt(1)
	v_pk_add_f32 v[28:29], v[92:93], v[28:29]
	s_waitcnt lgkmcnt(0)
	v_pk_add_f32 v[26:27], v[90:91], v[26:27]
	v_lshl_add_u64 v[36:37], v[34:35], 2, s[8:9]
	s_and_b64 vcc, exec, s[4:5]
	v_mov_b32_e32 v38, 0
	global_store_dwordx4 v[36:37], v[30:33], off sc1
	global_store_dwordx4 v[36:37], v[26:29], off offset:16 sc1
	s_cbranch_vccnz .LBB0_1223
	v_cvt_pk_bf16_f32 v38, v30, v31
	v_cvt_pk_bf16_f32 v39, v32, v33
	v_lshl_add_u64 v[42:43], v[34:35], 1, s[12:13]
	v_pk_mul_f32 v[32:33], v[32:33], v[32:33]
	v_pk_mul_f32 v[30:31], v[30:31], v[30:31]
	v_cvt_pk_bf16_f32 v40, v26, v27
	v_cvt_pk_bf16_f32 v41, v28, v29
	global_store_dwordx4 v[42:43], v[38:41], off sc1
	v_pk_mul_f32 v[28:29], v[28:29], v[28:29]
	v_pk_mul_f32 v[26:27], v[26:27], v[26:27]
	v_pk_mov_b32 v[38:39], v[30:31], v[32:33] op_sel:[1,0]
	v_mov_b32_e32 v31, v33
	v_pk_add_f32 v[30:31], v[38:39], v[30:31]
	v_mov_b32_e32 v32, v28
	v_mov_b32_e32 v33, v26
	v_mov_b32_e32 v26, v29
	v_pk_add_f32 v[26:27], v[32:33], v[26:27]
	v_add_f32_e32 v28, v30, v31
	v_add_f32_e32 v27, v28, v27
	v_add_f32_e32 v38, v26, v27
.LBB0_1223:
	ds_bpermute_b32 v22, v233, v22
	ds_bpermute_b32 v23, v233, v23
	ds_bpermute_b32 v24, v233, v24
	ds_bpermute_b32 v25, v233, v25
	ds_bpermute_b32 v18, v233, v18
	ds_bpermute_b32 v20, v233, v20
	ds_bpermute_b32 v21, v233, v21
	ds_bpermute_b32 v19, v233, v19
	s_waitcnt vmcnt(14) lgkmcnt(4)
	v_pk_add_f32 v[24:25], v[88:89], v[24:25]
	v_pk_add_f32 v[22:23], v[86:87], v[22:23]
	s_and_b64 vcc, exec, s[4:5]
	s_waitcnt lgkmcnt(1)
	v_pk_add_f32 v[20:21], v[84:85], v[20:21]
	s_waitcnt lgkmcnt(0)
	v_pk_add_f32 v[18:19], v[82:83], v[18:19]
	global_store_dwordx4 v[36:37], v[22:25], off offset:512 sc1
	global_store_dwordx4 v[36:37], v[18:21], off offset:528 sc1
	s_cbranch_vccnz .LBB0_1227
	v_mul_f32_e32 v27, v23, v23
	v_mul_f32_e32 v28, v25, v25
	v_fmac_f32_e32 v27, v22, v22
	v_fmac_f32_e32 v28, v24, v24
	v_add_f32_e32 v27, v27, v28
	v_mul_f32_e32 v28, v19, v19
	v_mul_f32_e32 v26, v21, v21
	v_fmac_f32_e32 v28, v18, v18
	v_fmac_f32_e32 v26, v20, v20
	v_add_f32_e32 v27, v27, v28
	v_add_f32_e32 v26, v26, v27
	v_and_b32_e32 v27, 64, v225
	v_add_f32_e32 v28, v38, v26
	v_xor_b32_e32 v26, 1, v225
	v_add_u32_e32 v29, 64, v27
	v_cmp_lt_i32_e32 vcc, v26, v29
	v_cvt_pk_bf16_f32 v22, v22, v23
	v_cvt_pk_bf16_f32 v23, v24, v25
	v_cvt_pk_bf16_f32 v24, v18, v19
	v_xor_b32_e32 v19, 2, v225
	v_cvt_pk_bf16_f32 v25, v20, v21
	s_nop 0
	v_cndmask_b32_e32 v26, v225, v26, vcc
	v_lshlrev_b32_e32 v26, 2, v26
	ds_bpermute_b32 v30, v26, v28
	v_cmp_lt_i32_e32 vcc, v19, v29
	v_lshlrev_b64 v[26:27], 1, v[34:35]
	v_or_b32_e32 v26, 0x100, v26
	v_cndmask_b32_e32 v19, v225, v19, vcc
	s_waitcnt lgkmcnt(0)
	v_add_f32_e32 v18, v28, v30
	v_lshlrev_b32_e32 v19, 2, v19
	ds_bpermute_b32 v19, v19, v18
	v_lshl_add_u64 v[20:21], s[12:13], 0, v[26:27]
	global_store_dwordx4 v[20:21], v[22:25], off sc1
	s_and_saveexec_b64 s[28:29], s[0:1]
	s_cbranch_execz .LBB0_1226
	v_readlane_b32 s44, v253, 34
	v_lshlrev_b64 v[20:21], 7, v[124:125]
	v_readlane_b32 s45, v253, 35
	v_lshl_add_u64 v[20:21], s[14:15], 0, v[20:21]
	s_mov_b32 s19, s45
	v_lshl_add_u64 v[20:21], s[26:27], 2, v[20:21]
	s_lshl_b32 s44, s40, 2
	v_writelane_b32 v253, s18, 34
	v_lshl_add_u64 v[20:21], v[20:21], 0, s[44:45]
	s_waitcnt lgkmcnt(0)
	v_add_f32_e32 v18, v18, v19
	v_writelane_b32 v253, s19, 35
	global_store_dword v[20:21], v18, off

; #define GAS __attribute__((address_space(1)))
; __device__ __forceinline__ unsigned pk2(float lo, float hi) { unsigned r; asm("v_cvt_pk_bf16_f32 %0, %1, %2" : "=v"(r) : "v"(lo), "v"(hi)); return r; }
; __device__ __forceinline__ f32x4 bperm_f4(int src4, f32x4 v) { return (f32x4){bperm_f(src4, v.x), bperm_f(src4, v.y), bperm_f(src4, v.z), bperm_f(src4, v.w)}; }
;     __device__ __forceinline__ void operator()(const pg8::f32x4 (&acc)[2][2][4][2], const pg8::Unit& u, int wr, int wc, int fr, int fq) const {
;     ...
;             for (int m = 0; m < 4; ++m) {
;                 const int row = row0 + ai * 128 + m * 16; float ss = 0.f;
; #pragma unroll
;                 for (int bj = 0; bj < 2; ++bj) {
;                     const size_t off = (size_t)row * DM + col0 + bj * 128;
;                     const f32x4 x0 = xo[m][bj][0] + bperm_f4(src4, acc[ai][bj][m][0]), x1 = xo[m][bj][1] + bperm_f4(src4, acc[ai][bj][m][1]);
;                     *(GAS f32x4*)(out + off) = x0; *(GAS f32x4*)(out + off + 4) = x1;
;                     if (XN) { u32x4 w; w.x = pk2(x0.x, x0.y); w.y = pk2(x0.z, x0.w); w.z = pk2(x1.x, x1.y); w.w = pk2(x1.z, x1.w); *(GAS u32x4*)(XN + off) = w;
;                         ss += (x0.x * x0.x + x0.y * x0.y) + (x0.z * x0.z + x0.w * x0.w) + (x1.x * x1.x + x1.y * x1.y) + (x1.z * x1.z + x1.w * x1.w); }
;                 }
;                 if (XN) { ss += __shfl_xor(ss, 1); ss += __shfl_xor(ss, 2); if ((fr & 3) == 0) ((GAS float*)RS)[(size_t)row * 32 + u.pn * 4 + wc] = ss; }
.LBB0_1227:
	ds_bpermute_b32 v14, v233, v14
	ds_bpermute_b32 v15, v233, v15
	ds_bpermute_b32 v16, v233, v16
	ds_bpermute_b32 v17, v233, v17
	ds_bpermute_b32 v10, v233, v10
	ds_bpermute_b32 v11, v233, v11
	ds_bpermute_b32 v12, v233, v12
	ds_bpermute_b32 v13, v233, v13
	s_waitcnt lgkmcnt(8)
	v_lshlrev_b64 v[18:19], 11, v[122:123]
	v_lshl_add_u64 v[18:19], v[18:19], 0, v[204:205]
	s_waitcnt vmcnt(14) lgkmcnt(4)
	v_pk_add_f32 v[16:17], v[80:81], v[16:17]
	v_pk_add_f32 v[14:15], v[78:79], v[14:15]
	s_waitcnt lgkmcnt(0)
	v_pk_add_f32 v[12:13], v[76:77], v[12:13]
	v_pk_add_f32 v[10:11], v[74:75], v[10:11]
	v_lshl_add_u64 v[20:21], v[18:19], 2, s[8:9]
	v_mov_b32_e32 v22, 0
	s_and_b64 vcc, exec, s[4:5]
	global_store_dwordx4 v[20:21], v[14:17], off sc1
	global_store_dwordx4 v[20:21], v[10:13], off offset:16 sc1
	s_cbranch_vccnz .LBB0_1229
	v_cvt_pk_bf16_f32 v22, v14, v15
	v_cvt_pk_bf16_f32 v23, v16, v17
	v_lshl_add_u64 v[26:27], v[18:19], 1, s[12:13]
	v_pk_mul_f32 v[16:17], v[16:17], v[16:17]
	v_pk_mul_f32 v[14:15], v[14:15], v[14:15]
	v_cvt_pk_bf16_f32 v24, v10, v11
	v_cvt_pk_bf16_f32 v25, v12, v13
	global_store_dwordx4 v[26:27], v[22:25], off sc1
	v_pk_mul_f32 v[12:13], v[12:13], v[12:13]
	v_pk_mul_f32 v[10:11], v[10:11], v[10:11]
	v_pk_mov_b32 v[22:23], v[14:15], v[16:17] op_sel:[1,0]
	v_mov_b32_e32 v15, v17
	v_pk_add_f32 v[14:15], v[22:23], v[14:15]
	v_mov_b32_e32 v16, v12
	v_mov_b32_e32 v17, v10
	v_mov_b32_e32 v10, v13
	v_pk_add_f32 v[10:11], v[16:17], v[10:11]
	v_add_f32_e32 v12, v14, v15
	v_add_f32_e32 v11, v12, v11
	v_add_f32_e32 v22, v10, v11
.LBB0_1229:
	ds_bpermute_b32 v6, v233, v6
	ds_bpermute_b32 v7, v233, v7
	ds_bpermute_b32 v8, v233, v8
	ds_bpermute_b32 v9, v233, v9
	ds_bpermute_b32 v2, v233, v2
	ds_bpermute_b32 v4, v233, v4
	ds_bpermute_b32 v5, v233, v5
	ds_bpermute_b32 v3, v233, v3
	s_waitcnt vmcnt(14) lgkmcnt(4)
	v_pk_add_f32 v[8:9], v[72:73], v[8:9]
	v_pk_add_f32 v[6:7], v[70:71], v[6:7]
	s_and_b64 vcc, exec, s[4:5]
	s_waitcnt lgkmcnt(1)
	v_pk_add_f32 v[4:5], v[68:69], v[4:5]
	s_waitcnt lgkmcnt(0)
	v_pk_add_f32 v[2:3], v[66:67], v[2:3]
	global_store_dwordx4 v[20:21], v[6:9], off offset:512 sc1
	global_store_dwordx4 v[20:21], v[2:5], off offset:528 sc1
	s_cbranch_vccnz .LBB0_1233
	v_mul_f32_e32 v11, v7, v7
	v_mul_f32_e32 v12, v9, v9
	v_fmac_f32_e32 v11, v6, v6
	v_fmac_f32_e32 v12, v8, v8
	v_add_f32_e32 v11, v11, v12
	v_mul_f32_e32 v12, v3, v3
	v_mul_f32_e32 v10, v5, v5
	v_fmac_f32_e32 v12, v2, v2
	v_fmac_f32_e32 v10, v4, v4
	v_add_f32_e32 v11, v11, v12
	v_add_f32_e32 v10, v10, v11
	v_and_b32_e32 v11, 64, v225
	v_add_f32_e32 v12, v22, v10
	v_xor_b32_e32 v10, 1, v225
	v_add_u32_e32 v13, 64, v11
	v_cmp_lt_i32_e32 vcc, v10, v13
	v_cvt_pk_bf16_f32 v6, v6, v7
	v_cvt_pk_bf16_f32 v7, v8, v9
	v_cvt_pk_bf16_f32 v8, v2, v3
	v_xor_b32_e32 v3, 2, v225
	v_cvt_pk_bf16_f32 v9, v4, v5
	s_nop 0
	v_cndmask_b32_e32 v10, v225, v10, vcc
	v_lshlrev_b32_e32 v10, 2, v10
	ds_bpermute_b32 v14, v10, v12
	v_cmp_lt_i32_e32 vcc, v3, v13
	v_lshlrev_b64 v[10:11], 1, v[18:19]
	v_or_b32_e32 v10, 0x100, v10
	v_cndmask_b32_e32 v3, v225, v3, vcc
	s_waitcnt lgkmcnt(0)
	v_add_f32_e32 v2, v12, v14
	v_lshlrev_b32_e32 v3, 2, v3
	ds_bpermute_b32 v3, v3, v2
	v_lshl_add_u64 v[4:5], s[12:13], 0, v[10:11]
	global_store_dwordx4 v[4:5], v[6:9], off sc1
	s_and_saveexec_b64 s[4:5], s[0:1]
	s_cbranch_execz .LBB0_1232
	v_lshlrev_b64 v[4:5], 7, v[122:123]
	v_lshl_add_u64 v[4:5], s[14:15], 0, v[4:5]
	v_lshl_add_u64 v[4:5], s[26:27], 2, v[4:5]
	v_readlane_b32 s26, v253, 34
	v_readlane_b32 s27, v253, 35
	s_mov_b32 s19, s27
	s_lshl_b32 s26, s40, 2
	v_writelane_b32 v253, s18, 34
	v_lshl_add_u64 v[4:5], v[4:5], 0, s[26:27]
	s_waitcnt lgkmcnt(0)
	v_add_f32_e32 v2, v2, v3
	v_writelane_b32 v253, s19, 35
	global_store_dword v[4:5], v2, off
